# 7.3 store widening: dilated-attention epilogue 8 x dwordx2 row-per-lane stores -> 4 x dwordx4 via v_permlane32_swap pairs (same bytes, same addresses)
# baseline (speedup 1.0000x reference)
.LBB0_509:
	v_cndmask_b32_e64 v16, v16, v225, s[38:39]
	v_cndmask_b32_e64 v17, v225, v17, s[4:5]
	v_exp_f32_e32 v240, v16
	v_cndmask_b32_e64 v18, v18, v225, s[40:41]
	v_exp_f32_e32 v239, v17
	v_cndmask_b32_e64 v19, v19, v225, s[42:43]
	v_exp_f32_e32 v238, v18
	v_cndmask_b32_e64 v20, v20, v225, s[44:45]
	v_exp_f32_e32 v237, v19
	v_cndmask_b32_e64 v21, v21, v225, s[46:47]
	v_exp_f32_e32 v236, v20
	v_add_f32_e32 v16, v240, v178
	v_cndmask_b32_e64 v22, v22, v225, s[48:49]
	v_exp_f32_e32 v235, v21
	v_add_f32_e32 v16, v239, v16
	v_cndmask_b32_e64 v23, v23, v225, s[50:51]
	v_exp_f32_e32 v234, v22
	v_add_f32_e32 v16, v238, v16
	v_cndmask_b32_e64 v24, v24, v225, s[52:53]
	v_exp_f32_e32 v233, v23
	v_add_f32_e32 v16, v237, v16
	v_cndmask_b32_e64 v25, v25, v225, s[54:55]
	v_exp_f32_e32 v232, v24
	v_add_f32_e32 v16, v236, v16
	v_cndmask_b32_e64 v26, v26, v225, s[56:57]
	v_exp_f32_e32 v231, v25
	v_add_f32_e32 v16, v235, v16
	v_cndmask_b32_e64 v27, v27, v225, s[58:59]
	v_exp_f32_e32 v230, v26
	v_add_f32_e32 v16, v234, v16
	v_cndmask_b32_e64 v28, v28, v225, s[60:61]
	v_exp_f32_e32 v229, v27
	v_add_f32_e32 v16, v233, v16
	v_cndmask_b32_e64 v29, v29, v225, s[62:63]
	v_exp_f32_e32 v185, v28
	v_add_f32_e32 v16, v232, v16
	v_cndmask_b32_e64 v30, v30, v225, s[64:65]
	v_exp_f32_e32 v183, v29
	v_add_f32_e32 v16, v231, v16
	v_cndmask_b32_e64 v31, v31, v225, s[66:67]
	v_exp_f32_e32 v181, v30
	v_add_f32_e32 v16, v230, v16
	v_exp_f32_e32 v179, v31
	v_add_f32_e32 v16, v229, v16
	v_add_f32_e32 v16, v185, v16
	v_add_f32_e32 v16, v183, v16
	v_add_f32_e32 v16, v181, v16
	v_and_b32_e32 v17, 64, v228
	v_add_f32_e32 v60, v179, v16
	v_xor_b32_e32 v16, 32, v228
	v_add_u32_e32 v17, 64, v17
	v_cmp_lt_i32_e32 vcc, v16, v17
	v_cvt_pk_bf16_f32 v17, v164, v165
	v_cvt_pk_bf16_f32 v18, v167, v170
	v_cndmask_b32_e32 v16, v228, v16, vcc
	v_lshlrev_b32_e32 v178, 2, v16
	v_cvt_pk_bf16_f32 v16, v106, v107
	v_cvt_pk_bf16_f32 v19, v172, v174
	ds_read_b64_tr_b16 v[24:25], v188
	ds_read_b64_tr_b16 v[26:27], v188 offset:512
	ds_read_b64_tr_b16 v[20:21], v195
	ds_read_b64_tr_b16 v[22:23], v195 offset:512
	s_waitcnt lgkmcnt(0)
	v_cvt_pk_bf16_f32 v164, v166, v168
	v_cvt_pk_bf16_f32 v165, v169, v171
	v_mfma_f32_32x32x16_bf16 v[32:47], v[24:27], v[16:19], 0
	v_cvt_pk_bf16_f32 v166, v173, v175
	v_cvt_pk_bf16_f32 v167, v176, v177
	ds_read_b64_tr_b16 v[172:173], v196
	ds_read_b64_tr_b16 v[174:175], v196 offset:512
	ds_read_b64_tr_b16 v[168:169], v197
	ds_read_b64_tr_b16 v[170:171], v197 offset:512
	s_waitcnt lgkmcnt(0)
	v_cvt_pk_bf16_f32 v80, v105, v80
	v_cvt_pk_bf16_f32 v81, v81, v82
	v_cvt_pk_bf16_f32 v82, v83, v84
	v_cvt_pk_bf16_f32 v83, v85, v86
	v_mfma_f32_32x32x16_bf16 v[16:31], v[20:23], v[16:19], 0
	v_cvt_pk_bf16_f32 v66, v65, v66
	v_cvt_pk_bf16_f32 v67, v67, v68
	v_cvt_pk_bf16_f32 v68, v69, v70
	v_cvt_pk_bf16_f32 v69, v71, v72
	v_cvt_pk_bf16_f32 v48, v48, v49
	v_cvt_pk_bf16_f32 v49, v50, v51
	v_cvt_pk_bf16_f32 v50, v52, v53
	v_mfma_f32_32x32x16_bf16 v[32:47], v[172:175], v[164:167], v[32:47]
	v_cvt_pk_bf16_f32 v51, v54, v55
	s_ashr_i32 s95, s94, 31
	v_mfma_f32_32x32x16_bf16 v[16:31], v[168:171], v[164:167], v[16:31]
	ds_read_b64_tr_b16 v[168:169], v198
	ds_read_b64_tr_b16 v[170:171], v198 offset:512
	ds_read_b64_tr_b16 v[164:165], v199
	ds_read_b64_tr_b16 v[166:167], v199 offset:512
	s_waitcnt lgkmcnt(0)
	s_nop 0
	v_mfma_f32_32x32x16_bf16 v[32:47], v[168:171], v[80:83], v[32:47]
	v_mfma_f32_32x32x16_bf16 v[16:31], v[164:167], v[80:83], v[16:31]
	ds_read_b64_tr_b16 v[164:165], v200
	ds_read_b64_tr_b16 v[166:167], v200 offset:512
	ds_read_b64_tr_b16 v[80:81], v201
	ds_read_b64_tr_b16 v[82:83], v201 offset:512
	s_waitcnt lgkmcnt(0)
	s_nop 0
	v_mfma_f32_32x32x16_bf16 v[32:47], v[164:167], v[66:69], v[32:47]
	v_mfma_f32_32x32x16_bf16 v[16:31], v[80:83], v[66:69], v[16:31]
	v_cvt_pk_bf16_f32 v66, v73, v74
	v_cvt_pk_bf16_f32 v67, v75, v76
	v_cvt_pk_bf16_f32 v68, v77, v78
	v_cvt_pk_bf16_f32 v69, v79, v87
	ds_read_b64_tr_b16 v[74:75], v202
	ds_read_b64_tr_b16 v[76:77], v202 offset:512
	ds_read_b64_tr_b16 v[70:71], v203
	ds_read_b64_tr_b16 v[72:73], v203 offset:512
	s_waitcnt lgkmcnt(0)
	s_nop 1
	v_mfma_f32_32x32x16_bf16 v[32:47], v[74:77], v[66:69], v[32:47]
	v_mfma_f32_32x32x16_bf16 v[16:31], v[70:73], v[66:69], v[16:31]
	ds_read_b64_tr_b16 v[66:67], v204
	ds_read_b64_tr_b16 v[68:69], v204 offset:512
	ds_read_b64_tr_b16 v[52:53], v205
	ds_read_b64_tr_b16 v[54:55], v205 offset:512
	s_waitcnt lgkmcnt(0)
	s_nop 0
	v_mfma_f32_32x32x16_bf16 v[32:47], v[66:69], v[48:51], v[32:47]
	v_mfma_f32_32x32x16_bf16 v[16:31], v[52:55], v[48:51], v[16:31]
	v_cvt_pk_bf16_f32 v48, v64, v56
	v_cvt_pk_bf16_f32 v49, v57, v58
	v_cvt_pk_bf16_f32 v50, v61, v63
	v_cvt_pk_bf16_f32 v51, v89, v91
	ds_read_b64_tr_b16 v[64:65], v206
	ds_read_b64_tr_b16 v[66:67], v206 offset:512
	ds_read_b64_tr_b16 v[52:53], v207
	ds_read_b64_tr_b16 v[54:55], v207 offset:512
	s_waitcnt lgkmcnt(0)
	s_nop 1
	v_mfma_f32_32x32x16_bf16 v[32:47], v[64:67], v[48:51], v[32:47]
	v_mfma_f32_32x32x16_bf16 v[16:31], v[52:55], v[48:51], v[16:31]
	v_cvt_pk_bf16_f32 v48, v59, v62
	v_cvt_pk_bf16_f32 v49, v88, v90
	v_cvt_pk_bf16_f32 v50, v92, v93
	v_cvt_pk_bf16_f32 v51, v94, v95
	ds_read_b64_tr_b16 v[56:57], v208
	ds_read_b64_tr_b16 v[58:59], v208 offset:512
	ds_read_b64_tr_b16 v[52:53], v209
	ds_read_b64_tr_b16 v[54:55], v209 offset:512
	s_waitcnt lgkmcnt(0)
	s_nop 1
	v_mfma_f32_32x32x16_bf16 v[32:47], v[56:59], v[48:51], v[32:47]
	v_mfma_f32_32x32x16_bf16 v[16:31], v[52:55], v[48:51], v[16:31]
	v_cvt_pk_bf16_f32 v48, v240, v239
	v_cvt_pk_bf16_f32 v49, v238, v237
	v_cvt_pk_bf16_f32 v50, v236, v235
	v_cvt_pk_bf16_f32 v51, v234, v233
	ds_read_b64_tr_b16 v[56:57], v210
	ds_read_b64_tr_b16 v[58:59], v210 offset:512
	ds_read_b64_tr_b16 v[52:53], v211
	ds_read_b64_tr_b16 v[54:55], v211 offset:512
	s_waitcnt lgkmcnt(0)
	s_nop 1
	v_mfma_f32_32x32x16_bf16 v[32:47], v[56:59], v[48:51], v[32:47]
	v_mfma_f32_32x32x16_bf16 v[16:31], v[52:55], v[48:51], v[16:31]
	v_cvt_pk_bf16_f32 v48, v232, v231
	v_cvt_pk_bf16_f32 v49, v230, v229
	v_cvt_pk_bf16_f32 v50, v185, v183
	v_cvt_pk_bf16_f32 v51, v181, v179
	ds_read_b64_tr_b16 v[56:57], v212
	ds_read_b64_tr_b16 v[58:59], v212 offset:512
	ds_read_b64_tr_b16 v[52:53], v213
	ds_read_b64_tr_b16 v[54:55], v213 offset:512
	s_waitcnt lgkmcnt(0)
	v_mov_b32_e32 v185, v104
	s_nop 0
	v_mfma_f32_32x32x16_bf16 v[32:47], v[56:59], v[48:51], v[32:47]
	v_mfma_f32_32x32x16_bf16 v[16:31], v[52:55], v[48:51], v[16:31]
	ds_bpermute_b32 v48, v178, v60
	s_waitcnt lgkmcnt(0)
	v_add_f32_e32 v50, v60, v48
	s_lshl_b64 s[6:7], s[94:95], 12
	s_add_u32 s6, s6, s77
	s_addc_u32 s7, s7, 0
	v_rcp_f32_e32 v52, v50
	s_nop 0
	v_lshl_add_u32 v48, s93, 8, v194
	v_ashrrev_i32_e32 v49, 31, v48
	v_lshlrev_b64 v[48:49], s8, v[48:49]
	s_ashr_i32 s77, s76, 31
	v_lshl_add_u64 v[48:49], s[6:7], 0, v[48:49]
	s_lshl_b64 s[6:7], s[76:77], 24
	s_add_u32 s6, s9, s6
	s_addc_u32 s7, s33, s7
	v_lshlrev_b64 v[54:55], 10, v[48:49]
	v_lshl_add_u64 v[54:55], s[6:7], 0, v[54:55]
	s_lshl_b32 s6, s92, 7
	s_mov_b32 s7, s71
	v_lshl_add_u64 v[54:55], v[54:55], 0, s[6:7]
	v_lshl_add_u64 v[54:55], v[54:55], 0, v[184:185]
	v_and_b32_e32 v56, 32, v227
	v_mov_b32_e32 v57, 0
	v_lshrrev_b32_e32 v56, 2, v56
	v_pk_mul_f32 v[32:33], v[32:33], v[52:53] op_sel_hi:[1,0]
	v_pk_mul_f32 v[34:35], v[34:35], v[52:53] op_sel_hi:[1,0]
	v_pk_mul_f32 v[36:37], v[36:37], v[52:53] op_sel_hi:[1,0]
	v_pk_mul_f32 v[38:39], v[38:39], v[52:53] op_sel_hi:[1,0]
	v_pk_mul_f32 v[40:41], v[40:41], v[52:53] op_sel_hi:[1,0]
	v_pk_mul_f32 v[42:43], v[42:43], v[52:53] op_sel_hi:[1,0]
	v_pk_mul_f32 v[44:45], v[44:45], v[52:53] op_sel_hi:[1,0]
	v_pk_mul_f32 v[46:47], v[46:47], v[52:53] op_sel_hi:[1,0]
	v_pk_mul_f32 v[16:17], v[16:17], v[52:53] op_sel_hi:[1,0]
	v_pk_mul_f32 v[18:19], v[18:19], v[52:53] op_sel_hi:[1,0]
	v_pk_mul_f32 v[20:21], v[20:21], v[52:53] op_sel_hi:[1,0]
	v_pk_mul_f32 v[22:23], v[22:23], v[52:53] op_sel_hi:[1,0]
	v_pk_mul_f32 v[24:25], v[24:25], v[52:53] op_sel_hi:[1,0]
	v_pk_mul_f32 v[26:27], v[26:27], v[52:53] op_sel_hi:[1,0]
	v_pk_mul_f32 v[28:29], v[28:29], v[52:53] op_sel_hi:[1,0]
	v_pk_mul_f32 v[30:31], v[30:31], v[52:53] op_sel_hi:[1,0]
	v_lshl_add_u64 v[54:55], v[54:55], 0, v[56:57]
	v_cvt_pk_bf16_f32 v32, v32, v33
	v_cvt_pk_bf16_f32 v33, v34, v35
	v_cvt_pk_bf16_f32 v34, v36, v37
	v_cvt_pk_bf16_f32 v35, v38, v39
	v_cvt_pk_bf16_f32 v36, v40, v41
	v_cvt_pk_bf16_f32 v37, v42, v43
	v_cvt_pk_bf16_f32 v38, v44, v45
	v_cvt_pk_bf16_f32 v39, v46, v47
	v_cvt_pk_bf16_f32 v16, v16, v17
	v_cvt_pk_bf16_f32 v17, v18, v19
	v_cvt_pk_bf16_f32 v18, v20, v21
	v_cvt_pk_bf16_f32 v19, v22, v23
	v_cvt_pk_bf16_f32 v20, v24, v25
	v_cvt_pk_bf16_f32 v21, v26, v27
	v_cvt_pk_bf16_f32 v22, v28, v29
	v_cvt_pk_bf16_f32 v23, v30, v31
	s_nop 1
	v_permlane32_swap_b32_e32 v32, v34
	v_permlane32_swap_b32_e32 v33, v35
	v_permlane32_swap_b32_e32 v36, v38
	v_permlane32_swap_b32_e32 v37, v39
	v_permlane32_swap_b32_e32 v16, v18
	v_permlane32_swap_b32_e32 v17, v19
	v_permlane32_swap_b32_e32 v20, v22
	v_permlane32_swap_b32_e32 v21, v23
	global_store_dwordx4 v[54:55], v[16:19], off offset:64
	global_store_dwordx4 v[54:55], v[20:23], off offset:96
	global_store_dwordx4 v[54:55], v[32:35], off
	global_store_dwordx4 v[54:55], v[36:39], off offset:32
	s_nop 1
	s_and_saveexec_b64 s[6:7], s[68:69]
	s_cbranch_execz .LBB0_490
	v_log_f32_e32 v16, v50
	s_lshl_b64 s[74:75], s[76:77], 19
	s_add_u32 s74, s10, s74
	s_addc_u32 s75, s11, s75
	v_add_f32_e32 v16, v187, v16
	v_mul_f32_e32 v18, 0x3f317218, v16
	v_lshlrev_b64 v[16:17], 5, v[48:49]
	s_mov_b32 s93, s71
	v_lshl_add_u64 v[16:17], s[74:75], 0, v[16:17]
	v_lshl_add_u64 v[16:17], s[92:93], 2, v[16:17]
	global_store_dword v[16:17], v18, off
	s_branch .LBB0_490
